# v153 with the six next-item loads spread across the scan steps (one per 16 VALU) and the V image written first
# speedup vs baseline: 1.0090x; 1.0025x over previous
.LBB0_867:
	s_waitcnt vmcnt(4)
	s_add_i32 s91, s90, 1
	s_cmp_ge_i32 s91, s88
	s_cselect_b64 s[22:23], -1, 0
	s_cmp_lg_u32 s91, s99
	s_cselect_b32 s8, s98, 0
	s_andn2_b32 s8, s8, s22
	s_cmp_lg_u32 s8, 0
	s_cbranch_scc0 .Lf1_prep_slow
	v_cvt_f32_f16 v28, v24
	v_lshrrev_b32_e32 v0, 16, v24
	v_cvt_f32_f16 v29, v0
	v_cvt_f32_f16 v30, v25
	v_lshrrev_b32_e32 v0, 16, v25
	v_cvt_f32_f16 v31, v0
	v_cvt_f32_f16 v32, v26
	v_lshrrev_b32_e32 v0, 16, v26
	v_cvt_f32_f16 v33, v0
	v_cvt_f32_f16 v34, v27
	v_lshrrev_b32_e32 v0, 16, v27
	v_cvt_f32_f16 v35, v0
	v_mul_f32_e32 v28, 0x3fb8aa3b, v28
	v_mul_f32_e32 v29, 0x3fb8aa3b, v29
	v_mul_f32_e32 v30, 0x3fb8aa3b, v30
	v_mul_f32_e32 v31, 0x3fb8aa3b, v31
	v_mul_f32_e32 v32, 0x3fb8aa3b, v32
	v_mul_f32_e32 v33, 0x3fb8aa3b, v33
	v_mul_f32_e32 v34, 0x3fb8aa3b, v34
	v_mul_f32_e32 v35, 0x3fb8aa3b, v35
	v_lshl_add_u64 v[230:231], v[230:231], 0, s[30:31]
	global_load_dwordx4 v[24:27], v[230:231], off
	ds_write_b128 v142, v[12:15] offset:36864
	v_lshl_add_u64 v[224:225], v[224:225], 0, s[30:31]
	global_load_dwordx4 v[12:15], v[224:225], off
	v_add_f32_dpp v28, v28, v28 row_shr:1 row_mask:0xf bank_mask:0xf bound_ctrl:1
	v_lshlrev_b32_e32 v68, 16, v16
	v_add_f32_dpp v29, v29, v29 row_shr:1 row_mask:0xf bank_mask:0xf bound_ctrl:1
	v_and_b32_e32 v69, 0xffff0000, v16
	v_add_f32_dpp v30, v30, v30 row_shr:1 row_mask:0xf bank_mask:0xf bound_ctrl:1
	v_lshlrev_b32_e32 v70, 16, v17
	v_add_f32_dpp v31, v31, v31 row_shr:1 row_mask:0xf bank_mask:0xf bound_ctrl:1
	v_and_b32_e32 v71, 0xffff0000, v17
	v_add_f32_dpp v32, v32, v32 row_shr:1 row_mask:0xf bank_mask:0xf bound_ctrl:1
	v_lshlrev_b32_e32 v72, 16, v18
	v_add_f32_dpp v33, v33, v33 row_shr:1 row_mask:0xf bank_mask:0xf bound_ctrl:1
	v_and_b32_e32 v73, 0xffff0000, v18
	v_add_f32_dpp v34, v34, v34 row_shr:1 row_mask:0xf bank_mask:0xf bound_ctrl:1
	v_lshlrev_b32_e32 v74, 16, v19
	v_add_f32_dpp v35, v35, v35 row_shr:1 row_mask:0xf bank_mask:0xf bound_ctrl:1
	v_and_b32_e32 v75, 0xffff0000, v19
	v_lshl_add_u64 v[226:227], v[226:227], 0, s[30:31]
	global_load_dwordx4 v[16:19], v[226:227], off
	v_add_f32_dpp v28, v28, v28 row_shr:2 row_mask:0xf bank_mask:0xf bound_ctrl:1
	v_lshlrev_b32_e32 v76, 16, v4
	v_add_f32_dpp v29, v29, v29 row_shr:2 row_mask:0xf bank_mask:0xf bound_ctrl:1
	v_and_b32_e32 v77, 0xffff0000, v4
	v_add_f32_dpp v30, v30, v30 row_shr:2 row_mask:0xf bank_mask:0xf bound_ctrl:1
	v_lshlrev_b32_e32 v78, 16, v5
	v_add_f32_dpp v31, v31, v31 row_shr:2 row_mask:0xf bank_mask:0xf bound_ctrl:1
	v_and_b32_e32 v79, 0xffff0000, v5
	v_add_f32_dpp v32, v32, v32 row_shr:2 row_mask:0xf bank_mask:0xf bound_ctrl:1
	v_lshlrev_b32_e32 v80, 16, v6
	v_add_f32_dpp v33, v33, v33 row_shr:2 row_mask:0xf bank_mask:0xf bound_ctrl:1
	v_and_b32_e32 v81, 0xffff0000, v6
	v_add_f32_dpp v34, v34, v34 row_shr:2 row_mask:0xf bank_mask:0xf bound_ctrl:1
	v_lshlrev_b32_e32 v82, 16, v7
	v_add_f32_dpp v35, v35, v35 row_shr:2 row_mask:0xf bank_mask:0xf bound_ctrl:1
	v_and_b32_e32 v83, 0xffff0000, v7
	v_lshl_add_u64 v[220:221], v[220:221], 0, s[30:31]
	global_load_dwordx4 v[4:7], v[220:221], off
	v_add_f32_dpp v28, v28, v28 row_shr:4 row_mask:0xf bank_mask:0xf bound_ctrl:1
	v_lshlrev_b32_e32 v84, 16, v20
	v_add_f32_dpp v29, v29, v29 row_shr:4 row_mask:0xf bank_mask:0xf bound_ctrl:1
	v_and_b32_e32 v85, 0xffff0000, v20
	v_add_f32_dpp v30, v30, v30 row_shr:4 row_mask:0xf bank_mask:0xf bound_ctrl:1
	v_lshlrev_b32_e32 v86, 16, v21
	v_add_f32_dpp v31, v31, v31 row_shr:4 row_mask:0xf bank_mask:0xf bound_ctrl:1
	v_and_b32_e32 v87, 0xffff0000, v21
	v_add_f32_dpp v32, v32, v32 row_shr:4 row_mask:0xf bank_mask:0xf bound_ctrl:1
	v_lshlrev_b32_e32 v88, 16, v22
	v_add_f32_dpp v33, v33, v33 row_shr:4 row_mask:0xf bank_mask:0xf bound_ctrl:1
	v_and_b32_e32 v89, 0xffff0000, v22
	v_add_f32_dpp v34, v34, v34 row_shr:4 row_mask:0xf bank_mask:0xf bound_ctrl:1
	v_lshlrev_b32_e32 v90, 16, v23
	v_add_f32_dpp v35, v35, v35 row_shr:4 row_mask:0xf bank_mask:0xf bound_ctrl:1
	v_and_b32_e32 v91, 0xffff0000, v23
	v_lshl_add_u64 v[228:229], v[228:229], 0, s[30:31]
	global_load_dwordx4 v[20:23], v[228:229], off
	v_add_f32_dpp v28, v28, v28 row_shr:8 row_mask:0xf bank_mask:0xf bound_ctrl:1
	v_lshlrev_b32_e32 v92, 16, v8
	v_add_f32_dpp v29, v29, v29 row_shr:8 row_mask:0xf bank_mask:0xf bound_ctrl:1
	v_and_b32_e32 v93, 0xffff0000, v8
	v_add_f32_dpp v30, v30, v30 row_shr:8 row_mask:0xf bank_mask:0xf bound_ctrl:1
	v_lshlrev_b32_e32 v94, 16, v9
	v_add_f32_dpp v31, v31, v31 row_shr:8 row_mask:0xf bank_mask:0xf bound_ctrl:1
	v_and_b32_e32 v95, 0xffff0000, v9
	v_add_f32_dpp v32, v32, v32 row_shr:8 row_mask:0xf bank_mask:0xf bound_ctrl:1
	v_lshlrev_b32_e32 v96, 16, v10
	v_add_f32_dpp v33, v33, v33 row_shr:8 row_mask:0xf bank_mask:0xf bound_ctrl:1
	v_and_b32_e32 v97, 0xffff0000, v10
	v_add_f32_dpp v34, v34, v34 row_shr:8 row_mask:0xf bank_mask:0xf bound_ctrl:1
	v_lshlrev_b32_e32 v98, 16, v11
	v_add_f32_dpp v35, v35, v35 row_shr:8 row_mask:0xf bank_mask:0xf bound_ctrl:1
	v_and_b32_e32 v99, 0xffff0000, v11
	v_lshl_add_u64 v[222:223], v[222:223], 0, s[30:31]
	global_load_dwordx4 v[8:11], v[222:223], off
	v_add_f32_dpp v28, v28, v28 row_bcast:15 row_mask:0xa bank_mask:0xf
	v_add_f32_dpp v29, v29, v29 row_bcast:15 row_mask:0xa bank_mask:0xf
	v_add_f32_dpp v30, v30, v30 row_bcast:15 row_mask:0xa bank_mask:0xf
	v_add_f32_dpp v31, v31, v31 row_bcast:15 row_mask:0xa bank_mask:0xf
	v_add_f32_dpp v32, v32, v32 row_bcast:15 row_mask:0xa bank_mask:0xf
	v_add_f32_dpp v33, v33, v33 row_bcast:15 row_mask:0xa bank_mask:0xf
	v_add_f32_dpp v34, v34, v34 row_bcast:15 row_mask:0xa bank_mask:0xf
	v_add_f32_dpp v35, v35, v35 row_bcast:15 row_mask:0xa bank_mask:0xf
	v_add_f32_dpp v28, v28, v28 row_bcast:31 row_mask:0xc bank_mask:0xf
	v_add_f32_dpp v29, v29, v29 row_bcast:31 row_mask:0xc bank_mask:0xf
	v_add_f32_dpp v30, v30, v30 row_bcast:31 row_mask:0xc bank_mask:0xf
	v_add_f32_dpp v31, v31, v31 row_bcast:31 row_mask:0xc bank_mask:0xf
	v_add_f32_dpp v32, v32, v32 row_bcast:31 row_mask:0xc bank_mask:0xf
	v_add_f32_dpp v33, v33, v33 row_bcast:31 row_mask:0xc bank_mask:0xf
	v_add_f32_dpp v34, v34, v34 row_bcast:31 row_mask:0xc bank_mask:0xf
	v_add_f32_dpp v35, v35, v35 row_bcast:31 row_mask:0xc bank_mask:0xf
	v_exp_f32_e32 v36, v28
	v_exp_f32_e32 v37, v29
	v_exp_f32_e32 v38, v30
	v_exp_f32_e32 v39, v31
	v_exp_f32_e32 v40, v32
	v_exp_f32_e32 v41, v33
	v_exp_f32_e32 v42, v34
	v_exp_f32_e32 v43, v35
	v_exp_f32_e64 v44, -v28
	v_exp_f32_e64 v45, -v29
	v_exp_f32_e64 v46, -v30
	v_exp_f32_e64 v47, -v31
	v_exp_f32_e64 v48, -v32
	v_exp_f32_e64 v49, -v33
	v_exp_f32_e64 v50, -v34
	v_exp_f32_e64 v51, -v35
	v_mov_b32_dpp v212, v36 wave_shr:1 row_mask:0xf bank_mask:0xf
	v_mov_b32_dpp v213, v37 wave_shr:1 row_mask:0xf bank_mask:0xf
	v_mov_b32_dpp v214, v38 wave_shr:1 row_mask:0xf bank_mask:0xf
	v_mov_b32_dpp v215, v39 wave_shr:1 row_mask:0xf bank_mask:0xf
	v_mov_b32_dpp v216, v40 wave_shr:1 row_mask:0xf bank_mask:0xf
	v_mov_b32_dpp v217, v41 wave_shr:1 row_mask:0xf bank_mask:0xf
	v_mov_b32_dpp v218, v42 wave_shr:1 row_mask:0xf bank_mask:0xf
	v_mov_b32_dpp v219, v43 wave_shr:1 row_mask:0xf bank_mask:0xf
	v_readlane_b32 s9, v254, 60
	s_add_i32 s9, s9, 0x21c00
	v_mov_b32_e32 v0, s9
	s_mov_b64 s[84:85], exec
	s_andn2_b64 exec, exec, s[38:39]
	ds_write_b128 v0, v[36:39]
	ds_write_b128 v0, v[40:43] offset:16
	s_mov_b64 exec, s[84:85]
	v_pk_mul_f32 v[68:69], v[212:213], v[68:69] neg_lo:[0,1] neg_hi:[0,1]
	v_pk_mul_f32 v[70:71], v[214:215], v[70:71] neg_lo:[0,1] neg_hi:[0,1]
	v_pk_mul_f32 v[72:73], v[216:217], v[72:73] neg_lo:[0,1] neg_hi:[0,1]
	v_pk_mul_f32 v[74:75], v[218:219], v[74:75] neg_lo:[0,1] neg_hi:[0,1]
	v_pk_mul_f32 v[76:77], v[36:37], v[76:77]
	v_pk_mul_f32 v[78:79], v[38:39], v[78:79]
	v_pk_mul_f32 v[80:81], v[40:41], v[80:81]
	v_pk_mul_f32 v[82:83], v[42:43], v[82:83]
	v_pk_mul_f32 v[84:85], v[44:45], v[84:85]
	v_pk_mul_f32 v[86:87], v[46:47], v[86:87]
	v_pk_mul_f32 v[88:89], v[48:49], v[88:89]
	v_pk_mul_f32 v[90:91], v[50:51], v[90:91]
	v_pk_mul_f32 v[92:93], v[44:45], v[92:93]
	v_pk_mul_f32 v[94:95], v[46:47], v[94:95]
	v_pk_mul_f32 v[96:97], v[48:49], v[96:97]
	v_pk_mul_f32 v[98:99], v[50:51], v[98:99]
	v_cvt_pk_bf16_f32 v52, v68, v69
	v_cvt_pk_bf16_f32 v53, v70, v71
	v_cvt_pk_bf16_f32 v54, v72, v73
	v_cvt_pk_bf16_f32 v55, v74, v75
	v_cvt_pk_bf16_f32 v56, v76, v77
	v_cvt_pk_bf16_f32 v57, v78, v79
	v_cvt_pk_bf16_f32 v58, v80, v81
	v_cvt_pk_bf16_f32 v59, v82, v83
	ds_write_b128 v142, v[52:55]
	ds_write_b128 v142, v[56:59] offset:27648
	v_cvt_pk_bf16_f32 v60, v84, v85
	v_cvt_pk_bf16_f32 v61, v86, v87
	v_cvt_pk_bf16_f32 v62, v88, v89
	v_cvt_pk_bf16_f32 v63, v90, v91
	v_cvt_pk_bf16_f32 v64, v92, v93
	v_cvt_pk_bf16_f32 v65, v94, v95
	v_cvt_pk_bf16_f32 v66, v96, v97
	v_cvt_pk_bf16_f32 v67, v98, v99
	ds_write_b128 v142, v[60:63] offset:9216
	ds_write_b128 v142, v[64:67] offset:18432
	s_branch .LBB0_877
.Lf1_prep_slow:
	v_cvt_f32_f16 v28, v24
	v_lshrrev_b32_e32 v0, 16, v24
	v_cvt_f32_f16 v29, v0
	v_cvt_f32_f16 v30, v25
	v_lshrrev_b32_e32 v0, 16, v25
	v_cvt_f32_f16 v31, v0
	v_cvt_f32_f16 v32, v26
	v_lshrrev_b32_e32 v0, 16, v26
	v_cvt_f32_f16 v33, v0
	v_cvt_f32_f16 v34, v27
	v_lshrrev_b32_e32 v0, 16, v27
	v_cvt_f32_f16 v35, v0
	v_mul_f32_e32 v28, 0x3fb8aa3b, v28
	v_mul_f32_e32 v29, 0x3fb8aa3b, v29
	v_mul_f32_e32 v30, 0x3fb8aa3b, v30
	v_mul_f32_e32 v31, 0x3fb8aa3b, v31
	v_mul_f32_e32 v32, 0x3fb8aa3b, v32
	v_mul_f32_e32 v33, 0x3fb8aa3b, v33
	v_mul_f32_e32 v34, 0x3fb8aa3b, v34
	v_mul_f32_e32 v35, 0x3fb8aa3b, v35
	ds_write_b128 v142, v[12:15] offset:36864
	v_add_f32_dpp v28, v28, v28 row_shr:1 row_mask:0xf bank_mask:0xf bound_ctrl:1
	v_lshlrev_b32_e32 v68, 16, v16
	v_add_f32_dpp v29, v29, v29 row_shr:1 row_mask:0xf bank_mask:0xf bound_ctrl:1
	v_and_b32_e32 v69, 0xffff0000, v16
	v_add_f32_dpp v30, v30, v30 row_shr:1 row_mask:0xf bank_mask:0xf bound_ctrl:1
	v_lshlrev_b32_e32 v70, 16, v17
	v_add_f32_dpp v31, v31, v31 row_shr:1 row_mask:0xf bank_mask:0xf bound_ctrl:1
	v_and_b32_e32 v71, 0xffff0000, v17
	v_add_f32_dpp v32, v32, v32 row_shr:1 row_mask:0xf bank_mask:0xf bound_ctrl:1
	v_lshlrev_b32_e32 v72, 16, v18
	v_add_f32_dpp v33, v33, v33 row_shr:1 row_mask:0xf bank_mask:0xf bound_ctrl:1
	v_and_b32_e32 v73, 0xffff0000, v18
	v_add_f32_dpp v34, v34, v34 row_shr:1 row_mask:0xf bank_mask:0xf bound_ctrl:1
	v_lshlrev_b32_e32 v74, 16, v19
	v_add_f32_dpp v35, v35, v35 row_shr:1 row_mask:0xf bank_mask:0xf bound_ctrl:1
	v_and_b32_e32 v75, 0xffff0000, v19
	v_add_f32_dpp v28, v28, v28 row_shr:2 row_mask:0xf bank_mask:0xf bound_ctrl:1
	v_lshlrev_b32_e32 v76, 16, v4
	v_add_f32_dpp v29, v29, v29 row_shr:2 row_mask:0xf bank_mask:0xf bound_ctrl:1
	v_and_b32_e32 v77, 0xffff0000, v4
	v_add_f32_dpp v30, v30, v30 row_shr:2 row_mask:0xf bank_mask:0xf bound_ctrl:1
	v_lshlrev_b32_e32 v78, 16, v5
	v_add_f32_dpp v31, v31, v31 row_shr:2 row_mask:0xf bank_mask:0xf bound_ctrl:1
	v_and_b32_e32 v79, 0xffff0000, v5
	v_add_f32_dpp v32, v32, v32 row_shr:2 row_mask:0xf bank_mask:0xf bound_ctrl:1
	v_lshlrev_b32_e32 v80, 16, v6
	v_add_f32_dpp v33, v33, v33 row_shr:2 row_mask:0xf bank_mask:0xf bound_ctrl:1
	v_and_b32_e32 v81, 0xffff0000, v6
	v_add_f32_dpp v34, v34, v34 row_shr:2 row_mask:0xf bank_mask:0xf bound_ctrl:1
	v_lshlrev_b32_e32 v82, 16, v7
	v_add_f32_dpp v35, v35, v35 row_shr:2 row_mask:0xf bank_mask:0xf bound_ctrl:1
	v_and_b32_e32 v83, 0xffff0000, v7
	v_add_f32_dpp v28, v28, v28 row_shr:4 row_mask:0xf bank_mask:0xf bound_ctrl:1
	v_lshlrev_b32_e32 v84, 16, v20
	v_add_f32_dpp v29, v29, v29 row_shr:4 row_mask:0xf bank_mask:0xf bound_ctrl:1
	v_and_b32_e32 v85, 0xffff0000, v20
	v_add_f32_dpp v30, v30, v30 row_shr:4 row_mask:0xf bank_mask:0xf bound_ctrl:1
	v_lshlrev_b32_e32 v86, 16, v21
	v_add_f32_dpp v31, v31, v31 row_shr:4 row_mask:0xf bank_mask:0xf bound_ctrl:1
	v_and_b32_e32 v87, 0xffff0000, v21
	v_add_f32_dpp v32, v32, v32 row_shr:4 row_mask:0xf bank_mask:0xf bound_ctrl:1
	v_lshlrev_b32_e32 v88, 16, v22
	v_add_f32_dpp v33, v33, v33 row_shr:4 row_mask:0xf bank_mask:0xf bound_ctrl:1
	v_and_b32_e32 v89, 0xffff0000, v22
	v_add_f32_dpp v34, v34, v34 row_shr:4 row_mask:0xf bank_mask:0xf bound_ctrl:1
	v_lshlrev_b32_e32 v90, 16, v23
	v_add_f32_dpp v35, v35, v35 row_shr:4 row_mask:0xf bank_mask:0xf bound_ctrl:1
	v_and_b32_e32 v91, 0xffff0000, v23
	v_add_f32_dpp v28, v28, v28 row_shr:8 row_mask:0xf bank_mask:0xf bound_ctrl:1
	v_lshlrev_b32_e32 v92, 16, v8
	v_add_f32_dpp v29, v29, v29 row_shr:8 row_mask:0xf bank_mask:0xf bound_ctrl:1
	v_and_b32_e32 v93, 0xffff0000, v8
	v_add_f32_dpp v30, v30, v30 row_shr:8 row_mask:0xf bank_mask:0xf bound_ctrl:1
	v_lshlrev_b32_e32 v94, 16, v9
	v_add_f32_dpp v31, v31, v31 row_shr:8 row_mask:0xf bank_mask:0xf bound_ctrl:1
	v_and_b32_e32 v95, 0xffff0000, v9
	v_add_f32_dpp v32, v32, v32 row_shr:8 row_mask:0xf bank_mask:0xf bound_ctrl:1
	v_lshlrev_b32_e32 v96, 16, v10
	v_add_f32_dpp v33, v33, v33 row_shr:8 row_mask:0xf bank_mask:0xf bound_ctrl:1
	v_and_b32_e32 v97, 0xffff0000, v10
	v_add_f32_dpp v34, v34, v34 row_shr:8 row_mask:0xf bank_mask:0xf bound_ctrl:1
	v_lshlrev_b32_e32 v98, 16, v11
	v_add_f32_dpp v35, v35, v35 row_shr:8 row_mask:0xf bank_mask:0xf bound_ctrl:1
	v_and_b32_e32 v99, 0xffff0000, v11
	v_add_f32_dpp v28, v28, v28 row_bcast:15 row_mask:0xa bank_mask:0xf
	v_add_f32_dpp v29, v29, v29 row_bcast:15 row_mask:0xa bank_mask:0xf
	v_add_f32_dpp v30, v30, v30 row_bcast:15 row_mask:0xa bank_mask:0xf
	v_add_f32_dpp v31, v31, v31 row_bcast:15 row_mask:0xa bank_mask:0xf
	v_add_f32_dpp v32, v32, v32 row_bcast:15 row_mask:0xa bank_mask:0xf
	v_add_f32_dpp v33, v33, v33 row_bcast:15 row_mask:0xa bank_mask:0xf
	v_add_f32_dpp v34, v34, v34 row_bcast:15 row_mask:0xa bank_mask:0xf
	v_add_f32_dpp v35, v35, v35 row_bcast:15 row_mask:0xa bank_mask:0xf
	v_add_f32_dpp v28, v28, v28 row_bcast:31 row_mask:0xc bank_mask:0xf
	v_add_f32_dpp v29, v29, v29 row_bcast:31 row_mask:0xc bank_mask:0xf
	v_add_f32_dpp v30, v30, v30 row_bcast:31 row_mask:0xc bank_mask:0xf
	v_add_f32_dpp v31, v31, v31 row_bcast:31 row_mask:0xc bank_mask:0xf
	v_add_f32_dpp v32, v32, v32 row_bcast:31 row_mask:0xc bank_mask:0xf
	v_add_f32_dpp v33, v33, v33 row_bcast:31 row_mask:0xc bank_mask:0xf
	v_add_f32_dpp v34, v34, v34 row_bcast:31 row_mask:0xc bank_mask:0xf
	v_add_f32_dpp v35, v35, v35 row_bcast:31 row_mask:0xc bank_mask:0xf
	v_exp_f32_e32 v36, v28
	v_exp_f32_e32 v37, v29
	v_exp_f32_e32 v38, v30
	v_exp_f32_e32 v39, v31
	v_exp_f32_e32 v40, v32
	v_exp_f32_e32 v41, v33
	v_exp_f32_e32 v42, v34
	v_exp_f32_e32 v43, v35
	v_exp_f32_e64 v44, -v28
	v_exp_f32_e64 v45, -v29
	v_exp_f32_e64 v46, -v30
	v_exp_f32_e64 v47, -v31
	v_exp_f32_e64 v48, -v32
	v_exp_f32_e64 v49, -v33
	v_exp_f32_e64 v50, -v34
	v_exp_f32_e64 v51, -v35
	v_mov_b32_dpp v212, v36 wave_shr:1 row_mask:0xf bank_mask:0xf
	v_mov_b32_dpp v213, v37 wave_shr:1 row_mask:0xf bank_mask:0xf
	v_mov_b32_dpp v214, v38 wave_shr:1 row_mask:0xf bank_mask:0xf
	v_mov_b32_dpp v215, v39 wave_shr:1 row_mask:0xf bank_mask:0xf
	v_mov_b32_dpp v216, v40 wave_shr:1 row_mask:0xf bank_mask:0xf
	v_mov_b32_dpp v217, v41 wave_shr:1 row_mask:0xf bank_mask:0xf
	v_mov_b32_dpp v218, v42 wave_shr:1 row_mask:0xf bank_mask:0xf
	v_mov_b32_dpp v219, v43 wave_shr:1 row_mask:0xf bank_mask:0xf
	v_readlane_b32 s9, v254, 60
	s_add_i32 s9, s9, 0x21c00
	v_mov_b32_e32 v0, s9
	s_mov_b64 s[84:85], exec
	s_andn2_b64 exec, exec, s[38:39]
	ds_write_b128 v0, v[36:39]
	ds_write_b128 v0, v[40:43] offset:16
	s_mov_b64 exec, s[84:85]
	v_pk_mul_f32 v[68:69], v[212:213], v[68:69] neg_lo:[0,1] neg_hi:[0,1]
	v_pk_mul_f32 v[70:71], v[214:215], v[70:71] neg_lo:[0,1] neg_hi:[0,1]
	v_pk_mul_f32 v[72:73], v[216:217], v[72:73] neg_lo:[0,1] neg_hi:[0,1]
	v_pk_mul_f32 v[74:75], v[218:219], v[74:75] neg_lo:[0,1] neg_hi:[0,1]
	v_pk_mul_f32 v[76:77], v[36:37], v[76:77]
	v_pk_mul_f32 v[78:79], v[38:39], v[78:79]
	v_pk_mul_f32 v[80:81], v[40:41], v[80:81]
	v_pk_mul_f32 v[82:83], v[42:43], v[82:83]
	v_pk_mul_f32 v[84:85], v[44:45], v[84:85]
	v_pk_mul_f32 v[86:87], v[46:47], v[86:87]
	v_pk_mul_f32 v[88:89], v[48:49], v[88:89]
	v_pk_mul_f32 v[90:91], v[50:51], v[90:91]
	v_pk_mul_f32 v[92:93], v[44:45], v[92:93]
	v_pk_mul_f32 v[94:95], v[46:47], v[94:95]
	v_pk_mul_f32 v[96:97], v[48:49], v[96:97]
	v_pk_mul_f32 v[98:99], v[50:51], v[98:99]
	v_cvt_pk_bf16_f32 v52, v68, v69
	v_cvt_pk_bf16_f32 v53, v70, v71
	v_cvt_pk_bf16_f32 v54, v72, v73
	v_cvt_pk_bf16_f32 v55, v74, v75
	v_cvt_pk_bf16_f32 v56, v76, v77
	v_cvt_pk_bf16_f32 v57, v78, v79
	v_cvt_pk_bf16_f32 v58, v80, v81
	v_cvt_pk_bf16_f32 v59, v82, v83
	ds_write_b128 v142, v[52:55]
	ds_write_b128 v142, v[56:59] offset:27648
	v_cvt_pk_bf16_f32 v60, v84, v85
	v_cvt_pk_bf16_f32 v61, v86, v87
	v_cvt_pk_bf16_f32 v62, v88, v89
	v_cvt_pk_bf16_f32 v63, v90, v91
	v_cvt_pk_bf16_f32 v64, v92, v93
	v_cvt_pk_bf16_f32 v65, v94, v95
	v_cvt_pk_bf16_f32 v66, v96, v97
	v_cvt_pk_bf16_f32 v67, v98, v99
	ds_write_b128 v142, v[60:63] offset:9216
	ds_write_b128 v142, v[64:67] offset:18432
	s_and_b64 vcc, exec, s[22:23]
	s_cbranch_vccnz .LBB0_877
	s_mul_hi_i32 s8, s91, 0x3e0f83e1
	s_mov_b64 s[94:95], s[20:21]
	s_mov_b64 s[20:21], s[68:69]
	s_mov_b64 s[68:69], s[66:67]
	s_mov_b64 s[66:67], s[64:65]
	s_mov_b64 s[64:65], s[62:63]
	s_mov_b64 s[62:63], s[18:19]
	s_mov_b64 s[18:19], s[46:47]
	s_mov_b64 s[46:47], s[44:45]
	s_mov_b64 s[44:45], s[42:43]
	s_mov_b64 s[42:43], s[40:41]
	s_mov_b64 s[40:41], s[38:39]
	s_lshr_b32 s9, s8, 31
	s_ashr_i32 s39, s8, 5
	s_add_i32 s39, s39, s9
	s_mul_i32 s8, s39, 0xffffff7c
	s_add_i32 vcc_lo, s90, s8
	s_add_i32 s34, vcc_lo, 1
	s_ashr_i32 s35, s39, 5
	s_and_b32 s38, s39, 1
	s_cmp_eq_u32 s38, 0
	s_cselect_b64 s[84:85], -1, 0
	s_cmp_gt_i32 s34, 3
	s_mov_b64 s[86:87], -1
	s_mul_i32 s8, s39, 0x84
	s_cbranch_scc0 .LBB0_874
	s_add_i32 s9, s27, s8
	s_add_i32 vcc_lo, vcc_lo, -3
	s_and_b64 s[86:87], s[84:85], exec
	s_cselect_b32 s9, vcc_lo, s9
	s_lshl_b32 s86, s35, 13
	s_lshl_b32 s9, s9, 6
	s_add_i32 s9, s9, s86
	s_mov_b64 s[86:87], 0
